# MLA per-tile LDS-DMA issue (71 SALU + 6 pieces) moved from right after the tile barrier to behind the first eight K reads of the tile (runs under their LDS latency); stacked on the full stack
# speedup vs baseline: 1.0037x; 1.0005x over previous
.LBB0_1218:
	s_waitcnt vmcnt(6) lgkmcnt(0)
	s_barrier
	s_lshl_b32 s50, s93, 6
	s_cmp_gt_u32 s50, s57
	s_cbranch_scc1 .Lmla_skiptile
	s_mul_i32 s6, s55, 0xb400
	s_add_i32 s6, s6, 0
	v_add_u32_e32 v3, s6, v204
	v_add3_u32 v4, s6, v206, v207
	s_mov_b32 s51, 0
	s_mov_b64 s[6:7], -1
	s_branch .LBB0_1221

.LBB0_1221:
	s_or_b32 s86, s51, s50
	s_cmp_gt_u32 s86, s57
	s_cbranch_scc1 .LBB0_1220
	v_or_b32_e32 v5, s51, v203
	s_movk_i32 s87, 0x190
	v_mad_u32_u24 v5, v5, s87, v3
	ds_read_b128 v[6:9], v5
	ds_read_b128 v[10:13], v5 offset:32
	ds_read_b128 v[14:17], v5 offset:64
	ds_read_b128 v[216:219], v5 offset:96
	ds_read_b128 v[220:223], v5 offset:128
	ds_read_b128 v[224:227], v5 offset:160
	ds_read_b128 v[228:231], v5 offset:192
	ds_read_b128 v[232:235], v5 offset:224
	s_cmp_lg_u32 s51, 0
	s_cbranch_scc1 .Lmla_nodma
	s_cmp_gt_i32 s55, 0
	s_cselect_b32 s98, -1, 2
	s_add_i32 s100, s98, s55
	s_add_i32 s98, s93, 2
	s_min_u32 s98, s98, s56
	s_mul_i32 s99, s98, 0x60000
	s_add_u32 s86, s92, s99
	s_addc_u32 s87, s54, 0
	s_lshl_b32 s98, s98, 18
	s_add_u32 s98, s80, s98
	s_mul_i32 s100, s100, 0xb400
	s_addc_u32 s99, s81, 0
	s_add_i32 vcc_lo, s100, 0
	s_and_b64 s[100:101], s[30:31], exec
	s_cselect_b32 s101, s87, s99
	s_cselect_b32 s100, s86, s98
	v_lshl_add_u64 v[238:239], s[100:101], 0, v[166:167]
	s_add_i32 s100, vcc_lo, s20
	s_mov_b32 s101, m0
	s_mov_b32 m0, s100
	s_nop 0
	global_load_lds_dwordx4 v[238:239], off
	s_mov_b32 m0, s101
	s_and_b64 s[100:101], s[52:53], exec
	s_cselect_b32 s101, s87, s99
	s_cselect_b32 s100, s86, s98
	v_lshl_add_u64 v[238:239], s[100:101], 0, v[146:147]
	s_add_i32 s100, vcc_lo, s26
	s_mov_b32 s101, m0
	s_mov_b32 m0, s100
	s_nop 0
	global_load_lds_dwordx4 v[238:239], off
	s_mov_b32 m0, s101
	s_and_b64 s[100:101], s[72:73], exec
	s_cselect_b32 s101, s87, s99
	s_cselect_b32 s100, s86, s98
	v_lshl_add_u64 v[238:239], s[100:101], 0, v[148:149]
	s_add_i32 s100, vcc_lo, s36
	s_mov_b32 s101, m0
	s_mov_b32 m0, s100
	s_nop 0
	global_load_lds_dwordx4 v[238:239], off
	s_mov_b32 m0, s101
	s_and_b64 s[100:101], s[74:75], exec
	s_cselect_b32 s101, s87, s99
	s_cselect_b32 s100, s86, s98
	v_lshl_add_u64 v[238:239], s[100:101], 0, v[150:151]
	s_add_i32 s100, vcc_lo, s38
	s_mov_b32 s101, m0
	s_mov_b32 m0, s100
	s_nop 0
	global_load_lds_dwordx4 v[238:239], off
	s_mov_b32 m0, s101
	s_and_b64 s[100:101], s[76:77], exec
	s_cselect_b32 s101, s87, s99
	s_cselect_b32 s100, s86, s98
	v_lshl_add_u64 v[238:239], s[100:101], 0, v[168:169]
	s_add_i32 s100, vcc_lo, s88
	s_mov_b32 s101, m0
	s_mov_b32 m0, s100
	s_nop 0
	global_load_lds_dwordx4 v[238:239], off
	s_mov_b32 m0, s101
	s_add_i32 vcc_lo, vcc_lo, s90
	v_lshl_add_u64 v[238:239], s[98:99], 0, v[152:153]
	s_mov_b32 s98, m0
	s_mov_b32 m0, vcc_lo
	s_nop 0
	global_load_lds_dwordx4 v[238:239], off
	s_mov_b32 m0, s98
	s_or_b32 s86, s51, s50
.Lmla_nodma:
	s_waitcnt lgkmcnt(7)
	v_mfma_f32_32x32x16_bf16 v[82:97], v[6:9], v[98:101], 0
	ds_read_b128 v[6:9], v5 offset:256
	s_waitcnt lgkmcnt(7)
	v_mfma_f32_32x32x16_bf16 v[82:97], v[10:13], v[102:105], v[82:97]
	ds_read_b128 v[10:13], v5 offset:288
	s_waitcnt lgkmcnt(7)
	v_mfma_f32_32x32x16_bf16 v[82:97], v[14:17], v[106:109], v[82:97]
	ds_read_b128 v[14:17], v5 offset:320
	s_waitcnt lgkmcnt(7)
	v_mfma_f32_32x32x16_bf16 v[82:97], v[216:219], v[110:113], v[82:97]
	ds_read_b128 v[216:219], v5 offset:352
	s_waitcnt lgkmcnt(7)
	v_mfma_f32_32x32x16_bf16 v[82:97], v[220:223], v[114:117], v[82:97]
	s_or_b32 s87, s86, 31
	s_cmp_le_u32 s87, s24
	s_waitcnt lgkmcnt(6)
	v_mfma_f32_32x32x16_bf16 v[82:97], v[224:227], v[118:121], v[82:97]
	s_waitcnt lgkmcnt(5)
	v_mfma_f32_32x32x16_bf16 v[82:97], v[228:231], v[122:125], v[82:97]
	s_waitcnt lgkmcnt(4)
	v_mfma_f32_32x32x16_bf16 v[82:97], v[232:235], v[126:129], v[82:97]
	s_waitcnt lgkmcnt(3)
	v_mfma_f32_32x32x16_bf16 v[82:97], v[6:9], v[130:133], v[82:97]
	s_waitcnt lgkmcnt(2)
	v_mfma_f32_32x32x16_bf16 v[82:97], v[10:13], v[134:137], v[82:97]
	s_waitcnt lgkmcnt(1)
	v_mfma_f32_32x32x16_bf16 v[82:97], v[14:17], v[138:141], v[82:97]
	s_waitcnt lgkmcnt(0)
	v_mfma_f32_32x32x16_bf16 v[82:97], v[216:219], v[142:145], v[82:97]
	v_or_b32_e32 v235, s51, v205
	s_movk_i32 s98, 0x140
	v_mad_u32_u24 v235, v235, s98, v4
	ds_read_b64_tr_b16 v[238:239], v235 offset:25600
	ds_read_b64_tr_b16 v[240:241], v235 offset:28160
	ds_read_b64_tr_b16 v[242:243], v235 offset:30720
	ds_read_b64_tr_b16 v[244:245], v235 offset:33280
	ds_read_b64_tr_b16 v[246:247], v235 offset:25664
	ds_read_b64_tr_b16 v[248:249], v235 offset:28224
	s_cbranch_scc1 .LBB0_1224
	v_or_b32_e32 v5, s86, v208
	v_cmp_lt_u32_e32 vcc, v5, v213
	v_or_b32_e32 v6, 2, v5
	s_nop 7
	v_cndmask_b32_e32 v83, v212, v83, vcc
	v_cmp_le_u32_e32 vcc, v5, v213
	s_nop 1
	v_cndmask_b32_e32 v82, v212, v82, vcc
	v_cmp_le_u32_e32 vcc, v6, v213
	v_or_b32_e32 v6, 3, v5
	s_nop 0
	v_cndmask_b32_e32 v84, v212, v84, vcc
	v_cmp_le_u32_e32 vcc, v6, v213
	v_or_b32_e32 v6, 8, v5
	s_nop 0
	v_cndmask_b32_e32 v85, v212, v85, vcc
	v_cmp_le_u32_e32 vcc, v6, v213
	v_or_b32_e32 v6, 9, v5
	s_nop 0
	v_cndmask_b32_e32 v86, v212, v86, vcc
	v_cmp_le_u32_e32 vcc, v6, v213
	v_or_b32_e32 v6, 10, v5
	s_nop 0
	v_cndmask_b32_e32 v87, v212, v87, vcc
	v_cmp_le_u32_e32 vcc, v6, v213
	v_or_b32_e32 v6, 11, v5
	s_nop 0
	v_cndmask_b32_e32 v88, v212, v88, vcc
	v_cmp_le_u32_e32 vcc, v6, v213
	v_or_b32_e32 v6, 16, v5
	s_nop 0
	v_cndmask_b32_e32 v89, v212, v89, vcc
	v_cmp_le_u32_e32 vcc, v6, v213
	v_or_b32_e32 v6, 17, v5
	s_nop 0
	v_cndmask_b32_e32 v90, v212, v90, vcc
	v_cmp_le_u32_e32 vcc, v6, v213
	v_or_b32_e32 v6, 18, v5
	s_nop 0
	v_cndmask_b32_e32 v91, v212, v91, vcc
	v_cmp_le_u32_e32 vcc, v6, v213
	v_or_b32_e32 v6, 19, v5
	s_nop 0
	v_cndmask_b32_e32 v92, v212, v92, vcc
	v_cmp_le_u32_e32 vcc, v6, v213
	v_or_b32_e32 v6, 24, v5
	s_nop 0
	v_cndmask_b32_e32 v93, v212, v93, vcc
	v_cmp_le_u32_e32 vcc, v6, v213
	v_or_b32_e32 v6, 25, v5
	s_nop 0
	v_cndmask_b32_e32 v94, v212, v94, vcc
	v_cmp_le_u32_e32 vcc, v6, v213
	v_or_b32_e32 v6, 26, v5
	v_or_b32_e32 v5, 27, v5
	v_cndmask_b32_e32 v95, v212, v95, vcc
	v_cmp_le_u32_e32 vcc, v6, v213
	s_nop 1
	v_cndmask_b32_e32 v96, v212, v96, vcc
	v_cmp_le_u32_e32 vcc, v5, v213
	s_nop 1
	v_cndmask_b32_e32 v97, v212, v97, vcc

.LBB0_1226:
	v_sub_f32_e32 v6, v83, v215
	v_exp_f32_e32 v216, v6
	v_sub_f32_e32 v6, v84, v215
	v_exp_f32_e32 v217, v6
	v_sub_f32_e32 v6, v85, v215
	v_exp_f32_e32 v218, v6
	v_sub_f32_e32 v6, v86, v215
	v_exp_f32_e32 v219, v6
	v_sub_f32_e32 v6, v87, v215
	v_exp_f32_e32 v220, v6
	v_sub_f32_e32 v6, v88, v215
	v_exp_f32_e32 v221, v6
	v_sub_f32_e32 v6, v89, v215
	v_exp_f32_e32 v222, v6
	v_sub_f32_e32 v6, v90, v215
	v_exp_f32_e32 v90, v6
	v_sub_f32_e32 v6, v91, v215
	v_exp_f32_e32 v91, v6
	v_sub_f32_e32 v6, v92, v215
	v_exp_f32_e32 v92, v6
	v_sub_f32_e32 v6, v93, v215
	v_exp_f32_e32 v93, v6
	v_sub_f32_e32 v6, v94, v215
	v_exp_f32_e32 v94, v6
	v_sub_f32_e32 v6, v95, v215
	v_exp_f32_e32 v95, v6
	v_or_b32_e32 v6, s51, v205
	s_movk_i32 s51, 0x140
	v_sub_f32_e32 v5, v82, v215
	v_mad_u32_u24 v88, v6, s51, v4
	v_exp_f32_e32 v5, v5
	v_sub_f32_e32 v10, v96, v215
	v_exp_f32_e32 v96, v10
	v_cvt_pk_bf16_f32 v10, v5, v216
	v_cvt_pk_bf16_f32 v11, v217, v218
	v_cvt_pk_bf16_f32 v12, v219, v220
	v_cvt_pk_bf16_f32 v13, v221, v222
	s_waitcnt lgkmcnt(0)
	v_mfma_f32_32x32x16_bf16 v[66:81], v[238:241], v[10:13], v[66:81]
	v_sub_f32_e32 v6, v97, v215
	v_exp_f32_e32 v97, v6
	v_cvt_pk_bf16_f32 v6, v90, v91
	v_cvt_pk_bf16_f32 v7, v92, v93
	v_cvt_pk_bf16_f32 v8, v94, v95
	v_cvt_pk_bf16_f32 v9, v96, v97
	v_add_f32_e32 v5, 0, v5
	v_add_f32_e32 v5, v216, v5
	s_waitcnt lgkmcnt(1)
	v_mfma_f32_32x32x16_bf16 v[66:81], v[242:245], v[6:9], v[66:81]
	ds_read_b64_tr_b16 v[14:15], v88 offset:30784
	v_add_f32_e32 v5, v217, v5
	v_add_f32_e32 v5, v218, v5
	v_add_f32_e32 v5, v219, v5
	v_add_f32_e32 v5, v220, v5
	v_add_f32_e32 v5, v221, v5
	v_add_f32_e32 v5, v222, v5
	s_waitcnt lgkmcnt(1)
	v_mfma_f32_32x32x16_bf16 v[50:65], v[246:249], v[10:13], v[50:65]
	ds_read_b64_tr_b16 v[16:17], v88 offset:33344
	ds_read_b64_tr_b16 v[82:83], v88 offset:25728
	v_add_f32_e32 v5, v90, v5
	v_add_f32_e32 v5, v91, v5
	v_add_f32_e32 v5, v92, v5
	v_add_f32_e32 v5, v93, v5
	v_add_f32_e32 v5, v94, v5
	v_add_f32_e32 v5, v95, v5
	s_waitcnt lgkmcnt(1)
	v_mfma_f32_32x32x16_bf16 v[50:65], v[14:17], v[6:9], v[50:65]
	ds_read_b64_tr_b16 v[84:85], v88 offset:28288
	ds_read_b64_tr_b16 v[14:15], v88 offset:30848
	ds_read_b64_tr_b16 v[16:17], v88 offset:33408
	v_add_f32_e32 v5, v96, v5
	v_add_f32_e32 v5, v97, v5
	s_xor_b64 s[86:87], s[6:7], -1
	v_add_f32_e32 v214, v214, v5
	s_waitcnt lgkmcnt(2)
	v_mfma_f32_32x32x16_bf16 v[34:49], v[82:85], v[10:13], v[34:49]
	ds_read_b64_tr_b16 v[82:83], v88 offset:25792
	ds_read_b64_tr_b16 v[84:85], v88 offset:28352
	ds_read_b64_tr_b16 v[86:87], v88 offset:30912
	ds_read_b64_tr_b16 v[88:89], v88 offset:33472
	s_waitcnt lgkmcnt(2)
	v_mfma_f32_32x32x16_bf16 v[18:33], v[82:85], v[10:13], v[18:33]
	v_mfma_f32_32x32x16_bf16 v[34:49], v[14:17], v[6:9], v[34:49]
	s_waitcnt lgkmcnt(0)
	v_mfma_f32_32x32x16_bf16 v[18:33], v[86:89], v[6:9], v[18:33]
	s_mov_b32 s51, 32
	s_mov_b64 s[6:7], 0
	s_and_b64 vcc, exec, s[86:87]
	s_cbranch_vccz .LBB0_1221
	s_branch .LBB0_1227
.Lmla_skiptile:
	s_cmp_gt_i32 s55, 0
	s_cselect_b32 s98, -1, 2
	s_add_i32 s100, s98, s55
	s_add_i32 s98, s93, 2
	s_min_u32 s98, s98, s56
	s_mul_i32 s99, s98, 0x60000
	s_add_u32 s86, s92, s99
	s_addc_u32 s87, s54, 0
	s_lshl_b32 s98, s98, 18
	s_add_u32 s98, s80, s98
	s_mul_i32 s100, s100, 0xb400
	s_addc_u32 s99, s81, 0
	s_add_i32 vcc_lo, s100, 0
	s_and_b64 s[100:101], s[30:31], exec
	s_cselect_b32 s101, s87, s99
	s_cselect_b32 s100, s86, s98
	v_lshl_add_u64 v[238:239], s[100:101], 0, v[166:167]
	s_add_i32 s100, vcc_lo, s20
	s_mov_b32 s101, m0
	s_mov_b32 m0, s100
	s_nop 0
	global_load_lds_dwordx4 v[238:239], off
	s_mov_b32 m0, s101
	s_and_b64 s[100:101], s[52:53], exec
	s_cselect_b32 s101, s87, s99
	s_cselect_b32 s100, s86, s98
	v_lshl_add_u64 v[238:239], s[100:101], 0, v[146:147]
	s_add_i32 s100, vcc_lo, s26
	s_mov_b32 s101, m0
	s_mov_b32 m0, s100
	s_nop 0
	global_load_lds_dwordx4 v[238:239], off
	s_mov_b32 m0, s101
	s_and_b64 s[100:101], s[72:73], exec
	s_cselect_b32 s101, s87, s99
	s_cselect_b32 s100, s86, s98
	v_lshl_add_u64 v[238:239], s[100:101], 0, v[148:149]
	s_add_i32 s100, vcc_lo, s36
	s_mov_b32 s101, m0
	s_mov_b32 m0, s100
	s_nop 0
	global_load_lds_dwordx4 v[238:239], off
	s_mov_b32 m0, s101
	s_and_b64 s[100:101], s[74:75], exec
	s_cselect_b32 s101, s87, s99
	s_cselect_b32 s100, s86, s98
	v_lshl_add_u64 v[238:239], s[100:101], 0, v[150:151]
	s_add_i32 s100, vcc_lo, s38
	s_mov_b32 s101, m0
	s_mov_b32 m0, s100
	s_nop 0
	global_load_lds_dwordx4 v[238:239], off
	s_mov_b32 m0, s101
	s_and_b64 s[100:101], s[76:77], exec
	s_cselect_b32 s101, s87, s99
	s_cselect_b32 s100, s86, s98
	v_lshl_add_u64 v[238:239], s[100:101], 0, v[168:169]
	s_add_i32 s100, vcc_lo, s88
	s_mov_b32 s101, m0
	s_mov_b32 m0, s100
	s_nop 0
	global_load_lds_dwordx4 v[238:239], off
	s_mov_b32 m0, s101
	s_add_i32 vcc_lo, vcc_lo, s90
	v_lshl_add_u64 v[238:239], s[98:99], 0, v[152:153]
	s_mov_b32 s98, m0
	s_mov_b32 m0, vcc_lo
	s_nop 0
	global_load_lds_dwordx4 v[238:239], off
	s_mov_b32 m0, s98
